# accumulator zero-init at tile start uses 32 v_mov_b64 instead of 64 v_mov_b32 in ffn_up and in-projection
# speedup vs baseline: 1.0295x; 1.0046x over previous
; #define LWRITE(RA, RB, BUF) do { char* w_ = wa + (BUF) * STAGE; _Pragma("unroll") for (int j = 0; j < NA; ++j) *(u32x4*)(w_ + j * 64 * PITCH) = RA[j]; _Pragma("unroll") for (int j = 0; j < NB; ++j) *(u32x4*)(w_ + AB + j * 64 * PITCH) = RB[j]; } while (0)
; #define LWRITE(RA, RB, BUF) do { char* w_ = wa + (BUF) * STAGE; _Pragma("unroll") for (int j = 0; j < NA; ++j) *(u32x4*)(w_ + j * 64 * RB_) = RA[j]; _Pragma("unroll") for (int j = 0; j < NB; ++j) *(u32x4*)(w_ + AB + j * 64 * RB_) = RB[j]; } while (0)
; template <bool SW, class AL, class BL>
; DI void gemm_run16(int tid, char* lds, const AL& al, const BL& bl, int nk, f32x4 (&acc)[4][4], u32x4 (&ra0)[4], u32x4 (&rb0)[2], u32x4 (&ra1)[4], u32x4 (&rb1)[2]) {
;     ...
;   LWRITE(ra0, rb0, 0);
;   __syncthreads();
; static __device__ __forceinline__ void phase_inproj(const P& p, int l, char* lds) {
;     ...
;     f32x4 acc[4][4];
; #pragma unroll
;     for (int a_ = 0; a_ < 4; ++a_)
; #pragma unroll
;       for (int b_ = 0; b_ < 4; ++b_) acc[a_][b_] = f32x4{0.f, 0.f, 0.f, 0.f};
;     __syncthreads();
;     gemm_run16<false>(tid, lds + LDS_SCR, al, bl, 16, acc, ra0, rb0, ra1, rb1);
.LBB0_288:
	v_mov_b64_e32 v[50:51], 0
	v_mov_b64_e32 v[52:53], 0
	v_mov_b64_e32 v[54:55], 0
	v_mov_b64_e32 v[56:57], 0
	v_mov_b64_e32 v[58:59], 0
	v_mov_b64_e32 v[60:61], 0
	v_mov_b64_e32 v[62:63], 0
	v_mov_b64_e32 v[64:65], 0
	v_mov_b64_e32 v[66:67], 0
	v_mov_b64_e32 v[68:69], 0
	v_mov_b64_e32 v[70:71], 0
	v_mov_b64_e32 v[72:73], 0
	v_mov_b64_e32 v[74:75], 0
	v_mov_b64_e32 v[76:77], 0
	v_mov_b64_e32 v[78:79], 0
	v_mov_b64_e32 v[80:81], 0
	v_mov_b64_e32 v[82:83], 0
	v_mov_b64_e32 v[84:85], 0
	v_mov_b64_e32 v[86:87], 0
	v_mov_b64_e32 v[88:89], 0
	v_mov_b64_e32 v[90:91], 0
	v_mov_b64_e32 v[92:93], 0
	v_mov_b64_e32 v[94:95], 0
	v_mov_b64_e32 v[96:97], 0
	v_mov_b64_e32 v[98:99], 0
	v_mov_b64_e32 v[100:101], 0
	v_mov_b64_e32 v[102:103], 0
	v_mov_b64_e32 v[104:105], 0
	v_mov_b64_e32 v[106:107], 0
	v_mov_b64_e32 v[108:109], 0
	v_mov_b64_e32 v[110:111], 0
	v_mov_b64_e32 v[112:113], 0
	s_mov_b32 s18, s22
	s_mov_b32 s19, s23
	s_mov_b32 s0, -2
	s_waitcnt vmcnt(4)
	s_barrier
	ds_write_b128 v203, v[26:29] offset:2304
	ds_write_b128 v203, v[30:33] offset:10496
	ds_write_b128 v203, v[34:37] offset:18688
	ds_write_b128 v203, v[42:45] offset:26880
	s_waitcnt vmcnt(3)
	ds_write_b128 v203, v[38:41] offset:35072
	s_waitcnt vmcnt(1)
	ds_write_b128 v203, v[46:49] offset:43264
	s_waitcnt vmcnt(0)
	ds_write_b128 v203, v[14:17] offset:51456
	ds_write_b128 v203, v[18:21] offset:59648
	ds_write_b128 v209, v[22:25]
	ds_write_b128 v210, v[6:9]
	ds_write_b128 v211, v[2:5]
	ds_write_b128 v212, v[10:13]
	s_waitcnt lgkmcnt(0)
	s_barrier

; static __device__ __forceinline__ void phase_ffn_up(const P& p, int l, char* lds) {
;     ...
;     f32x4 acc[4][4];
; #pragma unroll
;     for (int a_ = 0; a_ < 4; ++a_)
; #pragma unroll
;       for (int b_ = 0; b_ < 4; ++b_) acc[a_][b_] = f32x4{0.f, 0.f, 0.f, 0.f};
;     __syncthreads();
;     gemm_run16<false>(tid, lds + LDS_SCR, al, bl, 16, acc, ra0, rb0, ra1, rb1);
.LBB0_1059:
	v_mov_b64_e32 v[50:51], 0
	v_mov_b64_e32 v[52:53], 0
	v_mov_b64_e32 v[54:55], 0
	v_mov_b64_e32 v[56:57], 0
	v_mov_b64_e32 v[58:59], 0
	v_mov_b64_e32 v[60:61], 0
	v_mov_b64_e32 v[62:63], 0
	v_mov_b64_e32 v[64:65], 0
	v_mov_b64_e32 v[66:67], 0
	v_mov_b64_e32 v[68:69], 0
	v_mov_b64_e32 v[70:71], 0
	v_mov_b64_e32 v[72:73], 0
	v_mov_b64_e32 v[74:75], 0
	v_mov_b64_e32 v[76:77], 0
	v_mov_b64_e32 v[78:79], 0
	v_mov_b64_e32 v[80:81], 0
	v_mov_b64_e32 v[82:83], 0
	v_mov_b64_e32 v[84:85], 0
	v_mov_b64_e32 v[86:87], 0
	v_mov_b64_e32 v[88:89], 0
	v_mov_b64_e32 v[90:91], 0
	v_mov_b64_e32 v[92:93], 0
	v_mov_b64_e32 v[94:95], 0
	v_mov_b64_e32 v[96:97], 0
	v_mov_b64_e32 v[98:99], 0
	v_mov_b64_e32 v[100:101], 0
	v_mov_b64_e32 v[102:103], 0
	v_mov_b64_e32 v[104:105], 0
	v_mov_b64_e32 v[106:107], 0
	v_mov_b64_e32 v[108:109], 0
	v_mov_b64_e32 v[110:111], 0
	v_mov_b64_e32 v[112:113], 0
	s_mov_b32 s34, s31
	s_mov_b32 s35, s33
	s_mov_b32 s18, -2
	s_barrier
	s_waitcnt vmcnt(11)
	ds_write_b128 v141, v[26:29] offset:2304
	s_waitcnt vmcnt(9)
	ds_write_b128 v141, v[30:33] offset:10496
	s_waitcnt vmcnt(7)
	ds_write_b128 v141, v[34:37] offset:18688
	s_waitcnt vmcnt(5)
	ds_write_b128 v141, v[38:41] offset:26880
	s_waitcnt vmcnt(3)
	ds_write_b128 v141, v[42:45] offset:35072
	s_waitcnt vmcnt(1)
	ds_write_b128 v141, v[46:49] offset:43264
	s_waitcnt vmcnt(0)
	ds_write_b128 v141, v[14:17] offset:51456
	ds_write_b128 v141, v[18:21] offset:59648
	ds_write_b128 v146, v[22:25]
	ds_write_b128 v147, v[2:5]
	ds_write_b128 v148, v[6:9]
	ds_write_b128 v149, v[10:13]
	s_waitcnt lgkmcnt(0)
	s_barrier
